# attention: running-max subtraction of row group 0 folded into the QK MFMA accumulator input (C = -m block), 32 fewer VALU per key tile
# speedup vs baseline: 1.0095x; 1.0095x over previous
.LBB0_111:
	v_mov_b32_e32 v209, 0xf0c9f2ca
	v_cmp_lt_f32_e32 vcc, v227, v209
	s_nop 1
	v_cndmask_b32_e64 v208, v227, 0, vcc
	v_sub_f32_e32 v234, 0, v208
	v_sub_f32_e32 v235, 0, v208
	v_sub_f32_e32 v236, 0, v208
	v_sub_f32_e32 v237, 0, v208
	v_sub_f32_e32 v238, 0, v208
	v_sub_f32_e32 v239, 0, v208
	v_sub_f32_e32 v240, 0, v208
	v_sub_f32_e32 v241, 0, v208
	v_sub_f32_e32 v242, 0, v208
	v_sub_f32_e32 v243, 0, v208
	v_sub_f32_e32 v244, 0, v208
	v_sub_f32_e32 v245, 0, v208
	v_sub_f32_e32 v246, 0, v208
	v_sub_f32_e32 v247, 0, v208
	v_sub_f32_e32 v248, 0, v208
	v_sub_f32_e32 v249, 0, v208
	v_mov_b32_e32 v0, 0x80
	v_sub_u32_e64 v0, s28, v0 clamp
	s_lshr_b32 s3, s24, 2
	v_readfirstlane_b32 s8, v0
	s_lshr_b32 s18, s8, 6
	s_min_u32 s8, s28, 0xd80
	s_addk_i32 s8, 0x280
	s_lshr_b32 s10, s8, 6
	s_and_b64 s[8:9], s[16:17], exec
	s_cselect_b32 s10, s10, 64
	s_and_b64 s[8:9], s[38:39], exec
	s_cselect_b32 s8, s10, 0
	s_and_b64 s[40:41], s[16:17], s[38:39]
	s_and_b64 s[10:11], s[40:41], exec
	s_cselect_b32 s10, s18, 0
	s_lshl_b32 s2, s2, 2
	s_add_i32 s9, s2, s3
	s_sub_i32 s11, s8, s10
	s_mul_i32 s2, s9, 0x88000
	s_mul_hi_i32 s3, s9, 0x88000
	s_add_u32 s2, s31, s2
	s_addc_u32 s3, s46, s3
	s_sub_i32 s18, 64, s11
	s_cmp_gt_i32 s11, 0
	s_cselect_b32 s94, s10, s18
	s_lshl_b64 s[18:19], s[94:95], 13
	s_add_u32 s18, s2, s18
	s_addc_u32 s19, s3, s19
	v_lshl_add_u64 v[6:7], s[18:19], 0, v[190:191]
	v_lshlrev_b32_e32 v0, 1, v184
	v_mov_b32_e32 v3, 0x88000
	v_lshl_add_u64 v[8:9], v[6:7], 0, v[0:1]
	v_mad_i64_i32 v[6:7], s[18:19], s9, v3, v[192:193]
	s_lshl_b32 s94, s94, 7
	v_lshl_add_u64 v[10:11], v[6:7], 0, s[94:95]
	s_barrier
	v_lshl_add_u64 v[10:11], v[10:11], 0, v[0:1]
	global_load_dwordx4 v[176:179], v[8:9], off
	global_load_dwordx4 v[180:183], v[10:11], off
	s_cmp_lt_i32 s11, -2
	s_waitcnt vmcnt(1)
	ds_write_b128 v219, v[176:179]
	s_waitcnt vmcnt(0)
	ds_write_b128 v219, v[180:183] offset:9216
	s_cbranch_scc1 .LBB0_113
	s_or_b32 s9, s10, 1
	s_sub_i32 s18, 0x41, s11
	s_cmp_gt_i32 s11, 1
	s_cselect_b32 s94, s9, s18
	s_lshl_b64 s[18:19], s[94:95], 13
	s_add_u32 s18, s2, s18
	s_addc_u32 s19, s3, s19
	v_lshl_add_u64 v[8:9], s[18:19], 0, v[190:191]
	s_lshl_b32 s94, s94, 7
	v_lshl_add_u64 v[8:9], v[8:9], 0, v[0:1]
	v_lshl_add_u64 v[10:11], v[6:7], 0, s[94:95]
	v_lshl_add_u64 v[10:11], v[10:11], 0, v[0:1]
	global_load_dwordx4 v[176:179], v[8:9], off
	global_load_dwordx4 v[180:183], v[10:11], off

.LBB0_121:
	s_and_saveexec_b64 s[44:45], s[8:9]
	s_cbranch_execz .LBB0_131
	s_bitcmp1_b32 s49, 0
	s_cselect_b32 s8, 0x4800, 0
	s_add_i32 s8, s8, 16
	v_add3_u32 v0, s8, v186, v224
	ds_read_b128 v[2:5], v0
	s_and_b64 s[2:3], s[16:17], s[2:3]
	v_cndmask_b32_e64 v6, 0, 1, s[2:3]
	v_cmp_ne_u32_e64 s[38:39], 1, v6
	s_andn2_b64 vcc, exec, s[2:3]
	ds_read_b128 v[6:9], v0 offset:32
	ds_read_b128 v[10:13], v0 offset:64
	s_waitcnt lgkmcnt(2)
	v_mfma_f32_32x32x16_bf16 v[112:127], v[2:5], v[144:147], v[234:249]
	v_mfma_f32_32x32x16_bf16 v[96:111], v[2:5], v[160:163], 0
	ds_read_b128 v[2:5], v0 offset:96
	s_waitcnt lgkmcnt(2)
	v_mfma_f32_32x32x16_bf16 v[112:127], v[6:9], v[148:151], v[112:127]
	v_mfma_f32_32x32x16_bf16 v[96:111], v[6:9], v[164:167], v[96:111]
	ds_read_b128 v[6:9], v0 offset:4608
	s_waitcnt lgkmcnt(2)
	v_mfma_f32_32x32x16_bf16 v[112:127], v[10:13], v[152:155], v[112:127]
	v_mfma_f32_32x32x16_bf16 v[96:111], v[10:13], v[168:171], v[96:111]
	ds_read_b128 v[10:13], v0 offset:4640
	s_waitcnt lgkmcnt(2)
	v_mfma_f32_32x32x16_bf16 v[112:127], v[2:5], v[156:159], v[112:127]
	v_mfma_f32_32x32x16_bf16 v[96:111], v[2:5], v[172:175], v[96:111]
	ds_read_b128 v[2:5], v0 offset:4672
	s_waitcnt lgkmcnt(2)
	v_mfma_f32_32x32x16_bf16 v[128:143], v[6:9], v[144:147], v[234:249]
	v_mfma_f32_32x32x16_bf16 v[80:95], v[6:9], v[160:163], 0
	ds_read_b128 v[6:9], v0 offset:4704
	v_add_u32_e32 v0, s48, v221
	s_waitcnt lgkmcnt(2)
	v_mfma_f32_32x32x16_bf16 v[128:143], v[10:13], v[148:151], v[128:143]
	v_mfma_f32_32x32x16_bf16 v[80:95], v[10:13], v[164:167], v[80:95]
	s_waitcnt lgkmcnt(1)
	v_mfma_f32_32x32x16_bf16 v[128:143], v[2:5], v[152:155], v[128:143]
	v_mfma_f32_32x32x16_bf16 v[80:95], v[2:5], v[168:171], v[80:95]
	s_waitcnt lgkmcnt(0)
	v_mfma_f32_32x32x16_bf16 v[128:143], v[6:9], v[156:159], v[128:143]
	v_mfma_f32_32x32x16_bf16 v[80:95], v[6:9], v[172:175], v[80:95]
	s_cbranch_vccnz .LBB0_124
	v_sub_u32_e32 v2, v0, v229
	s_movk_i32 s0, 0xfefe
	v_cmp_lt_u32_e32 vcc, s0, v2
	v_add_u32_e32 v3, 1, v2
	s_nop 0
	v_cndmask_b32_e32 v112, v210, v112, vcc
	v_cmp_lt_u32_e32 vcc, s0, v3
	v_add_u32_e32 v3, 2, v2
	s_nop 0
	v_cndmask_b32_e32 v113, v210, v113, vcc
	v_cmp_lt_u32_e32 vcc, s0, v3
	v_add_u32_e32 v3, 3, v2
	s_nop 0
	v_cndmask_b32_e32 v114, v210, v114, vcc
	v_cmp_lt_u32_e32 vcc, s0, v3
	v_add_u32_e32 v3, 8, v2
	s_nop 0
	v_cndmask_b32_e32 v115, v210, v115, vcc
	v_cmp_lt_u32_e32 vcc, s0, v3
	v_add_u32_e32 v3, 9, v2
	s_nop 0
	v_cndmask_b32_e32 v116, v210, v116, vcc
	v_cmp_lt_u32_e32 vcc, s0, v3
	v_add_u32_e32 v3, 10, v2
	s_nop 0
	v_cndmask_b32_e32 v117, v210, v117, vcc
	v_cmp_lt_u32_e32 vcc, s0, v3
	v_add_u32_e32 v3, 11, v2
	s_nop 0
	v_cndmask_b32_e32 v118, v210, v118, vcc
	v_cmp_lt_u32_e32 vcc, s0, v3
	v_add_u32_e32 v3, 16, v2
	s_nop 0
	v_cndmask_b32_e32 v119, v210, v119, vcc
	v_cmp_lt_u32_e32 vcc, s0, v3
	v_add_u32_e32 v3, 17, v2
	s_nop 0
	v_cndmask_b32_e32 v120, v210, v120, vcc
	v_cmp_lt_u32_e32 vcc, s0, v3
	v_add_u32_e32 v3, 18, v2
	s_nop 0
	v_cndmask_b32_e32 v121, v210, v121, vcc
	v_cmp_lt_u32_e32 vcc, s0, v3
	v_add_u32_e32 v3, 19, v2
	s_nop 0
	v_cndmask_b32_e32 v122, v210, v122, vcc
	v_cmp_lt_u32_e32 vcc, s0, v3
	v_add_u32_e32 v3, 24, v2
	s_nop 0
	v_cndmask_b32_e32 v123, v210, v123, vcc
	v_cmp_lt_u32_e32 vcc, s0, v3
	v_add_u32_e32 v3, 25, v2
	s_nop 0
	v_cndmask_b32_e32 v124, v210, v124, vcc
	v_cmp_lt_u32_e32 vcc, s0, v3
	v_add_u32_e32 v3, 26, v2
	s_nop 0
	v_cndmask_b32_e32 v125, v210, v125, vcc
	v_cmp_lt_u32_e32 vcc, s0, v3
	v_add_u32_e32 v3, 27, v2
	s_nop 0
	v_cndmask_b32_e32 v126, v210, v126, vcc
	v_cmp_lt_u32_e32 vcc, s0, v3
	v_add_u32_e32 v3, 32, v2
	s_nop 0
	v_cndmask_b32_e32 v127, v210, v127, vcc
	v_cmp_lt_u32_e32 vcc, s0, v3
	v_add_u32_e32 v3, 33, v2
	s_nop 0
	v_cndmask_b32_e32 v128, v210, v128, vcc
	v_cmp_lt_u32_e32 vcc, s0, v3
	v_add_u32_e32 v3, 34, v2
	s_nop 0
	v_cndmask_b32_e32 v129, v210, v129, vcc
	v_cmp_lt_u32_e32 vcc, s0, v3
	v_add_u32_e32 v3, 35, v2
	s_nop 0
	v_cndmask_b32_e32 v130, v210, v130, vcc
	v_cmp_lt_u32_e32 vcc, s0, v3
	v_add_u32_e32 v3, 40, v2
	s_nop 0
	v_cndmask_b32_e32 v131, v210, v131, vcc
	v_cmp_lt_u32_e32 vcc, s0, v3
	v_add_u32_e32 v3, 41, v2
	s_nop 0
	v_cndmask_b32_e32 v132, v210, v132, vcc
	v_cmp_lt_u32_e32 vcc, s0, v3
	v_add_u32_e32 v3, 42, v2
	s_nop 0
	v_cndmask_b32_e32 v133, v210, v133, vcc
	v_cmp_lt_u32_e32 vcc, s0, v3
	v_add_u32_e32 v3, 43, v2
	s_nop 0
	v_cndmask_b32_e32 v134, v210, v134, vcc
	v_cmp_lt_u32_e32 vcc, s0, v3
	v_add_u32_e32 v3, 48, v2
	s_nop 0
	v_cndmask_b32_e32 v135, v210, v135, vcc
	v_cmp_lt_u32_e32 vcc, s0, v3
	v_add_u32_e32 v3, 49, v2
	s_nop 0
	v_cndmask_b32_e32 v136, v210, v136, vcc
	v_cmp_lt_u32_e32 vcc, s0, v3
	v_add_u32_e32 v3, 50, v2
	s_nop 0
	v_cndmask_b32_e32 v137, v210, v137, vcc
	v_cmp_lt_u32_e32 vcc, s0, v3
	v_add_u32_e32 v3, 51, v2
	s_nop 0
	v_cndmask_b32_e32 v138, v210, v138, vcc
	v_cmp_lt_u32_e32 vcc, s0, v3
	v_add_u32_e32 v3, 56, v2
	s_nop 0
	v_cndmask_b32_e32 v139, v210, v139, vcc
	v_cmp_lt_u32_e32 vcc, s0, v3
	v_add_u32_e32 v3, 57, v2
	s_nop 0
	v_cndmask_b32_e32 v140, v210, v140, vcc
	v_cmp_lt_u32_e32 vcc, s0, v3
	v_add_u32_e32 v3, 58, v2
	v_add_u32_e32 v2, 59, v2
	v_cndmask_b32_e32 v141, v210, v141, vcc
	v_cmp_lt_u32_e32 vcc, s0, v3
	s_nop 1
	v_cndmask_b32_e32 v142, v210, v142, vcc
	v_cmp_lt_u32_e32 vcc, s0, v2
	s_nop 1
	v_cndmask_b32_e32 v143, v210, v143, vcc
.LBB0_124:
	v_max_f32_e32 v2, v113, v113
	v_max_f32_e32 v3, v112, v112
	v_max_f32_e32 v2, v3, v2
	v_max3_f32 v2, v2, v114, v115
	v_max3_f32 v2, v2, v116, v117
	v_max3_f32 v2, v2, v118, v119
	v_max3_f32 v2, v2, v120, v121
	v_max3_f32 v2, v2, v122, v123
	v_max3_f32 v2, v2, v124, v125
	v_max3_f32 v2, v2, v126, v127
	v_max3_f32 v2, v2, v128, v129
	v_max3_f32 v2, v2, v130, v131
	v_max3_f32 v2, v2, v132, v133
	v_max3_f32 v2, v2, v134, v135
	v_max3_f32 v2, v2, v136, v137
	v_max3_f32 v2, v2, v138, v139
	v_max3_f32 v2, v2, v140, v141
	v_max3_f32 v2, v2, v142, v143
	v_add_f32_e32 v2, v2, v208
	v_add_f32_e32 v3, 0x41000000, v227
	v_cmp_gt_f32_e32 vcc, v2, v3
	s_cbranch_vccz .LBB0_126
	v_max_f32_e32 v2, v2, v2
	v_max_f32_e32 v3, v227, v227
	v_max_f32_e32 v2, v3, v2
	ds_bpermute_b32 v3, v222, v2
	s_waitcnt lgkmcnt(0)
	v_max_f32_e32 v3, v3, v3
	v_max_f32_e32 v3, v2, v3
	v_sub_f32_e32 v2, v227, v3
	v_exp_f32_e32 v2, v2
	v_mov_b32_e32 v227, v3
	v_mul_f32_e32 v199, v199, v2
	v_pk_mul_f32 v[78:79], v[78:79], v[2:3] op_sel_hi:[1,0]
	v_pk_mul_f32 v[76:77], v[76:77], v[2:3] op_sel_hi:[1,0]
	v_pk_mul_f32 v[74:75], v[74:75], v[2:3] op_sel_hi:[1,0]
	v_pk_mul_f32 v[72:73], v[72:73], v[2:3] op_sel_hi:[1,0]
	v_pk_mul_f32 v[70:71], v[70:71], v[2:3] op_sel_hi:[1,0]
	v_pk_mul_f32 v[68:69], v[68:69], v[2:3] op_sel_hi:[1,0]
	v_pk_mul_f32 v[66:67], v[66:67], v[2:3] op_sel_hi:[1,0]
	v_pk_mul_f32 v[64:65], v[64:65], v[2:3] op_sel_hi:[1,0]
	v_pk_mul_f32 v[62:63], v[62:63], v[2:3] op_sel_hi:[1,0]
	v_pk_mul_f32 v[60:61], v[60:61], v[2:3] op_sel_hi:[1,0]
	v_pk_mul_f32 v[58:59], v[58:59], v[2:3] op_sel_hi:[1,0]
	v_pk_mul_f32 v[56:57], v[56:57], v[2:3] op_sel_hi:[1,0]
	v_pk_mul_f32 v[54:55], v[54:55], v[2:3] op_sel_hi:[1,0]
	v_pk_mul_f32 v[52:53], v[52:53], v[2:3] op_sel_hi:[1,0]
	v_pk_mul_f32 v[50:51], v[50:51], v[2:3] op_sel_hi:[1,0]
	v_pk_mul_f32 v[48:49], v[48:49], v[2:3] op_sel_hi:[1,0]
	v_sub_f32_e32 v209, v227, v208
	v_mov_b32_e32 v208, v227
	v_sub_f32_e32 v112, v112, v209
	v_sub_f32_e32 v113, v113, v209
	v_sub_f32_e32 v114, v114, v209
	v_sub_f32_e32 v115, v115, v209
	v_sub_f32_e32 v116, v116, v209
	v_sub_f32_e32 v117, v117, v209
	v_sub_f32_e32 v118, v118, v209
	v_sub_f32_e32 v119, v119, v209
	v_sub_f32_e32 v120, v120, v209
	v_sub_f32_e32 v121, v121, v209
	v_sub_f32_e32 v122, v122, v209
	v_sub_f32_e32 v123, v123, v209
	v_sub_f32_e32 v124, v124, v209
	v_sub_f32_e32 v125, v125, v209
	v_sub_f32_e32 v126, v126, v209
	v_sub_f32_e32 v127, v127, v209
	v_sub_f32_e32 v128, v128, v209
	v_sub_f32_e32 v129, v129, v209
	v_sub_f32_e32 v130, v130, v209
	v_sub_f32_e32 v131, v131, v209
	v_sub_f32_e32 v132, v132, v209
	v_sub_f32_e32 v133, v133, v209
	v_sub_f32_e32 v134, v134, v209
	v_sub_f32_e32 v135, v135, v209
	v_sub_f32_e32 v136, v136, v209
	v_sub_f32_e32 v137, v137, v209
	v_sub_f32_e32 v138, v138, v209
	v_sub_f32_e32 v139, v139, v209
	v_sub_f32_e32 v140, v140, v209
	v_sub_f32_e32 v141, v141, v209
	v_sub_f32_e32 v142, v142, v209
	v_sub_f32_e32 v143, v143, v209
	v_sub_f32_e32 v234, 0, v208
	v_sub_f32_e32 v235, 0, v208
	v_sub_f32_e32 v236, 0, v208
	v_sub_f32_e32 v237, 0, v208
	v_sub_f32_e32 v238, 0, v208
	v_sub_f32_e32 v239, 0, v208
	v_sub_f32_e32 v240, 0, v208
	v_sub_f32_e32 v241, 0, v208
	v_sub_f32_e32 v242, 0, v208
	v_sub_f32_e32 v243, 0, v208
	v_sub_f32_e32 v244, 0, v208
	v_sub_f32_e32 v245, 0, v208
	v_sub_f32_e32 v246, 0, v208
	v_sub_f32_e32 v247, 0, v208
	v_sub_f32_e32 v248, 0, v208
	v_sub_f32_e32 v249, 0, v208
.LBB0_126:
	v_exp_f32_e32 v14, v112
	v_exp_f32_e32 v15, v113
	v_exp_f32_e32 v232, v114
	v_exp_f32_e32 v233, v115
	v_exp_f32_e32 v116, v116
	v_exp_f32_e32 v117, v117
	v_exp_f32_e32 v118, v118
	v_exp_f32_e32 v119, v119
	v_exp_f32_e32 v120, v120
	v_exp_f32_e32 v121, v121
	v_exp_f32_e32 v122, v122
	v_exp_f32_e32 v123, v123
	v_exp_f32_e32 v124, v124
	v_exp_f32_e32 v125, v125
	v_exp_f32_e32 v126, v126
	v_exp_f32_e32 v127, v127
	v_exp_f32_e32 v128, v128
	v_exp_f32_e32 v129, v129
	v_exp_f32_e32 v130, v130
	v_exp_f32_e32 v131, v131
	v_exp_f32_e32 v132, v132
	v_exp_f32_e32 v133, v133
	v_exp_f32_e32 v134, v134
	v_exp_f32_e32 v135, v135
	v_exp_f32_e32 v136, v136
	v_exp_f32_e32 v137, v137
	v_exp_f32_e32 v138, v138
	v_exp_f32_e32 v139, v139
	v_exp_f32_e32 v140, v140
	v_exp_f32_e32 v141, v141
	v_exp_f32_e32 v142, v142
	v_exp_f32_e32 v143, v143
	s_and_b64 vcc, exec, s[38:39]
	v_cvt_pk_bf16_f32 v112, v14, v15
	v_cvt_pk_bf16_f32 v113, v232, v233
	v_cvt_pk_bf16_f32 v114, v116, v117
	v_cvt_pk_bf16_f32 v115, v118, v119
	v_cvt_pk_bf16_f32 v10, v120, v121
	v_cvt_pk_bf16_f32 v11, v122, v123
	v_cvt_pk_bf16_f32 v12, v124, v125
	v_cvt_pk_bf16_f32 v13, v126, v127
	v_cvt_pk_bf16_f32 v6, v128, v129
	v_cvt_pk_bf16_f32 v7, v130, v131
	v_cvt_pk_bf16_f32 v8, v132, v133
	v_cvt_pk_bf16_f32 v9, v134, v135
	v_cvt_pk_bf16_f32 v2, v136, v137
	v_cvt_pk_bf16_f32 v3, v138, v139
	v_cvt_pk_bf16_f32 v4, v140, v141
	v_cvt_pk_bf16_f32 v5, v142, v143
	s_cbranch_vccnz .LBB0_128
	v_sub_u32_e32 v0, v0, v228
	s_movk_i32 s0, 0xfefe
	v_cmp_lt_u32_e32 vcc, s0, v0
	v_add_u32_e32 v197, 1, v0
	s_nop 0
	v_cndmask_b32_e32 v96, v210, v96, vcc
	v_cmp_lt_u32_e32 vcc, s0, v197
	v_add_u32_e32 v197, 2, v0
	s_nop 0
	v_cndmask_b32_e32 v97, v210, v97, vcc
	v_cmp_lt_u32_e32 vcc, s0, v197
	v_add_u32_e32 v197, 3, v0
	s_nop 0
	v_cndmask_b32_e32 v98, v210, v98, vcc
	v_cmp_lt_u32_e32 vcc, s0, v197
	v_add_u32_e32 v197, 8, v0
	s_nop 0
	v_cndmask_b32_e32 v99, v210, v99, vcc
	v_cmp_lt_u32_e32 vcc, s0, v197
	v_add_u32_e32 v197, 9, v0
	s_nop 0
	v_cndmask_b32_e32 v100, v210, v100, vcc
	v_cmp_lt_u32_e32 vcc, s0, v197
	v_add_u32_e32 v197, 10, v0
	s_nop 0
	v_cndmask_b32_e32 v101, v210, v101, vcc
	v_cmp_lt_u32_e32 vcc, s0, v197
	v_add_u32_e32 v197, 11, v0
	s_nop 0
	v_cndmask_b32_e32 v102, v210, v102, vcc
	v_cmp_lt_u32_e32 vcc, s0, v197
	v_add_u32_e32 v197, 16, v0
	s_nop 0
	v_cndmask_b32_e32 v103, v210, v103, vcc
	v_cmp_lt_u32_e32 vcc, s0, v197
	v_add_u32_e32 v197, 17, v0
	s_nop 0
	v_cndmask_b32_e32 v104, v210, v104, vcc
	v_cmp_lt_u32_e32 vcc, s0, v197
	v_add_u32_e32 v197, 18, v0
	s_nop 0
	v_cndmask_b32_e32 v105, v210, v105, vcc
	v_cmp_lt_u32_e32 vcc, s0, v197
	v_add_u32_e32 v197, 19, v0
	s_nop 0
	v_cndmask_b32_e32 v106, v210, v106, vcc
	v_cmp_lt_u32_e32 vcc, s0, v197
	v_add_u32_e32 v197, 24, v0
	s_nop 0
	v_cndmask_b32_e32 v107, v210, v107, vcc
	v_cmp_lt_u32_e32 vcc, s0, v197
	v_add_u32_e32 v197, 25, v0
	s_nop 0
	v_cndmask_b32_e32 v108, v210, v108, vcc
	v_cmp_lt_u32_e32 vcc, s0, v197
	v_add_u32_e32 v197, 26, v0
	s_nop 0
	v_cndmask_b32_e32 v109, v210, v109, vcc
	v_cmp_lt_u32_e32 vcc, s0, v197
	v_add_u32_e32 v197, 27, v0
	s_nop 0
	v_cndmask_b32_e32 v110, v210, v110, vcc
	v_cmp_lt_u32_e32 vcc, s0, v197
	v_add_u32_e32 v197, 32, v0
	s_nop 0
	v_cndmask_b32_e32 v111, v210, v111, vcc
	v_cmp_lt_u32_e32 vcc, s0, v197
	v_add_u32_e32 v197, 33, v0
	s_nop 0
	v_cndmask_b32_e32 v80, v210, v80, vcc
	v_cmp_lt_u32_e32 vcc, s0, v197
	v_add_u32_e32 v197, 34, v0
	s_nop 0
	v_cndmask_b32_e32 v81, v210, v81, vcc
	v_cmp_lt_u32_e32 vcc, s0, v197
	v_add_u32_e32 v197, 35, v0
	s_nop 0
	v_cndmask_b32_e32 v82, v210, v82, vcc
	v_cmp_lt_u32_e32 vcc, s0, v197
	v_add_u32_e32 v197, 40, v0
	s_nop 0
	v_cndmask_b32_e32 v83, v210, v83, vcc
	v_cmp_lt_u32_e32 vcc, s0, v197
	v_add_u32_e32 v197, 41, v0
	s_nop 0
	v_cndmask_b32_e32 v84, v210, v84, vcc
	v_cmp_lt_u32_e32 vcc, s0, v197
	v_add_u32_e32 v197, 42, v0
	s_nop 0
	v_cndmask_b32_e32 v85, v210, v85, vcc
	v_cmp_lt_u32_e32 vcc, s0, v197
	v_add_u32_e32 v197, 43, v0
	s_nop 0
	v_cndmask_b32_e32 v86, v210, v86, vcc
	v_cmp_lt_u32_e32 vcc, s0, v197
	v_add_u32_e32 v197, 48, v0
	s_nop 0
	v_cndmask_b32_e32 v87, v210, v87, vcc
	v_cmp_lt_u32_e32 vcc, s0, v197
	v_add_u32_e32 v197, 49, v0
	s_nop 0
	v_cndmask_b32_e32 v88, v210, v88, vcc
	v_cmp_lt_u32_e32 vcc, s0, v197
	v_add_u32_e32 v197, 50, v0
	s_nop 0
	v_cndmask_b32_e32 v89, v210, v89, vcc
	v_cmp_lt_u32_e32 vcc, s0, v197
	v_add_u32_e32 v197, 51, v0
	s_nop 0
	v_cndmask_b32_e32 v90, v210, v90, vcc
	v_cmp_lt_u32_e32 vcc, s0, v197
	v_add_u32_e32 v197, 56, v0
	s_nop 0
	v_cndmask_b32_e32 v91, v210, v91, vcc
	v_cmp_lt_u32_e32 vcc, s0, v197
	v_add_u32_e32 v197, 57, v0
	s_nop 0
	v_cndmask_b32_e32 v92, v210, v92, vcc
	v_cmp_lt_u32_e32 vcc, s0, v197
	v_add_u32_e32 v197, 58, v0
	v_add_u32_e32 v0, 59, v0
	v_cndmask_b32_e32 v93, v210, v93, vcc
	v_cmp_lt_u32_e32 vcc, s0, v197
	s_nop 1
	v_cndmask_b32_e32 v94, v210, v94, vcc
	v_cmp_lt_u32_e32 vcc, s0, v0
	s_nop 1
	v_cndmask_b32_e32 v95, v210, v95, vcc
